# GEMM unit heads: spurious s_waitcnt vmcnt(0) inside the accumulator zeroing removed (8 sites)
# baseline (speedup 1.0000x reference)
.LBB0_149:
	s_ashr_i32 s79, s78, 31
	s_lshl_b64 s[6:7], s[78:79], 11
	s_add_u32 s82, s34, s6
	s_addc_u32 s83, s35, s7
	s_and_b64 s[6:7], s[0:1], exec
	s_cselect_b32 s8, s83, s3
	s_cselect_b32 s9, s82, s2
	s_ashr_i32 s81, s80, 31
	s_lshl_b64 s[6:7], s[80:81], 11
	s_add_u32 s84, s40, s6
	s_addc_u32 s85, s41, s7
	s_and_b64 s[6:7], s[0:1], exec
	s_cselect_b32 s79, s85, s5
	s_cselect_b32 s81, s84, s4
	s_add_u32 s2, s2, 0x40080
	s_addc_u32 s3, s3, 0
	s_add_u32 s87, s4, 0x100
	v_mov_b32_e32 v0, 0
	s_addc_u32 s88, s5, 0
	s_mov_b32 s89, -2
	v_mov_b32_e32 v1, v0
	v_mov_b32_e32 v2, v0
	v_mov_b32_e32 v3, v0
	v_mov_b32_e32 v4, v0
	v_mov_b32_e32 v5, v0
	v_mov_b32_e32 v6, v0
	v_mov_b32_e32 v7, v0
	v_mov_b32_e32 v16, v0
	v_mov_b32_e32 v17, v0
	v_mov_b32_e32 v18, v0
	v_mov_b32_e32 v19, v0
	v_mov_b32_e32 v20, v0
	v_mov_b32_e32 v21, v0
	v_mov_b32_e32 v22, v0
	v_mov_b32_e32 v23, v0
	v_mov_b32_e32 v32, v0
	v_mov_b32_e32 v33, v0
	v_mov_b32_e32 v34, v0
	v_mov_b32_e32 v35, v0

	v_mov_b64_e32 v[8:9], 0
	v_mov_b64_e32 v[10:11], 0
	v_mov_b64_e32 v[12:13], 0
	v_mov_b64_e32 v[14:15], 0
	v_mov_b64_e32 v[24:25], 0
	v_mov_b64_e32 v[26:27], 0
	v_mov_b64_e32 v[28:29], 0
	v_mov_b64_e32 v[30:31], 0
	v_mov_b64_e32 v[36:37], 0
	v_mov_b64_e32 v[38:39], 0
	v_mov_b64_e32 v[40:41], 0
	v_mov_b64_e32 v[42:43], 0
	v_mov_b64_e32 v[44:45], 0
	v_mov_b64_e32 v[46:47], 0
	v_mov_b64_e32 v[64:65], 0
	v_mov_b64_e32 v[66:67], 0
	v_mov_b64_e32 v[68:69], 0
	v_mov_b64_e32 v[70:71], 0
	v_mov_b64_e32 v[72:73], 0
	v_mov_b64_e32 v[74:75], 0
	v_mov_b64_e32 v[76:77], 0
	v_mov_b64_e32 v[78:79], 0
	v_mov_b64_e32 v[80:81], 0
	v_mov_b64_e32 v[82:83], 0
	v_mov_b64_e32 v[84:85], 0
	v_mov_b64_e32 v[86:87], 0
	v_mov_b64_e32 v[88:89], 0
	v_mov_b64_e32 v[90:91], 0
	v_mov_b64_e32 v[92:93], 0
	v_mov_b64_e32 v[94:95], 0
	v_mov_b64_e32 v[96:97], 0
	v_mov_b64_e32 v[98:99], 0
	v_mov_b64_e32 v[100:101], 0
	v_mov_b64_e32 v[102:103], 0
	v_mov_b64_e32 v[104:105], 0
	v_mov_b64_e32 v[106:107], 0
	v_mov_b64_e32 v[108:109], 0
	v_mov_b64_e32 v[110:111], 0
	v_mov_b64_e32 v[112:113], 0
	v_mov_b64_e32 v[114:115], 0
	v_mov_b64_e32 v[116:117], 0
	v_mov_b64_e32 v[118:119], 0
	v_mov_b64_e32 v[120:121], 0
	v_mov_b64_e32 v[122:123], 0
	v_mov_b64_e32 v[124:125], 0
	v_mov_b64_e32 v[126:127], 0
	v_mov_b64_e32 v[128:129], 0
	v_mov_b64_e32 v[130:131], 0
	v_mov_b64_e32 v[132:133], 0
	v_mov_b64_e32 v[134:135], 0
	v_mov_b64_e32 v[136:137], 0
	v_mov_b64_e32 v[138:139], 0
	v_mov_b64_e32 v[140:141], 0
	v_mov_b64_e32 v[142:143], 0

.LBB0_740:
	s_ashr_i32 s11, s10, 31
	v_cmp_lt_i64_e32 vcc, s[14:15], v[164:165]
	s_lshl_b64 s[14:15], s[10:11], 11
	s_add_u32 s14, s41, s14
	s_addc_u32 s15, s54, s15
	s_and_b64 s[18:19], vcc, exec
	s_cselect_b32 s6, s15, s53
	s_cselect_b32 s11, s14, s52
	s_ashr_i32 s13, s12, 31
	s_lshl_b64 s[18:19], s[12:13], 11
	s_add_u32 s18, s55, s18
	s_addc_u32 s19, s56, s19
	s_and_b64 s[60:61], vcc, exec
	s_cselect_b32 s13, s19, s59
	s_cselect_b32 s80, s18, s58
	s_add_u32 s52, s52, 0x40080
	s_addc_u32 s53, s53, 0
	s_add_u32 s81, s58, 0x100
	v_mov_b32_e32 v0, 0
	s_addc_u32 s82, s59, 0
	s_mov_b32 s83, -2
	s_waitcnt lgkmcnt(0)
	v_mov_b32_e32 v1, v0
	v_mov_b32_e32 v2, v0
	v_mov_b32_e32 v3, v0
	v_mov_b32_e32 v4, v0
	v_mov_b32_e32 v5, v0
	v_mov_b32_e32 v6, v0
	v_mov_b32_e32 v7, v0
	v_mov_b32_e32 v16, v0
	v_mov_b32_e32 v17, v0
	v_mov_b32_e32 v18, v0
	v_mov_b32_e32 v19, v0
	v_mov_b32_e32 v20, v0
	v_mov_b32_e32 v21, v0
	v_mov_b32_e32 v22, v0
	v_mov_b32_e32 v23, v0
	v_mov_b32_e32 v32, v0
	v_mov_b32_e32 v33, v0
	v_mov_b32_e32 v34, v0
	v_mov_b32_e32 v35, v0

	v_mov_b64_e32 v[8:9], 0
	v_mov_b64_e32 v[10:11], 0
	v_mov_b64_e32 v[12:13], 0
	v_mov_b64_e32 v[14:15], 0
	v_mov_b64_e32 v[24:25], 0
	v_mov_b64_e32 v[26:27], 0
	v_mov_b64_e32 v[28:29], 0
	v_mov_b64_e32 v[30:31], 0
	v_mov_b64_e32 v[36:37], 0
	v_mov_b64_e32 v[38:39], 0
	v_mov_b64_e32 v[40:41], 0
	v_mov_b64_e32 v[42:43], 0
	v_mov_b64_e32 v[44:45], 0
	v_mov_b64_e32 v[46:47], 0
	v_mov_b64_e32 v[48:49], 0
	v_mov_b64_e32 v[50:51], 0
	v_mov_b64_e32 v[52:53], 0
	v_mov_b64_e32 v[54:55], 0
	v_mov_b64_e32 v[56:57], 0
	v_mov_b64_e32 v[58:59], 0
	v_mov_b64_e32 v[60:61], 0
	v_mov_b64_e32 v[62:63], 0
	v_mov_b64_e32 v[64:65], 0
	v_mov_b64_e32 v[66:67], 0
	v_mov_b64_e32 v[68:69], 0
	v_mov_b64_e32 v[70:71], 0
	v_mov_b64_e32 v[72:73], 0
	v_mov_b64_e32 v[74:75], 0
	v_mov_b64_e32 v[76:77], 0
	v_mov_b64_e32 v[78:79], 0
	v_mov_b64_e32 v[80:81], 0
	v_mov_b64_e32 v[82:83], 0
	v_mov_b64_e32 v[84:85], 0
	v_mov_b64_e32 v[86:87], 0
	v_mov_b64_e32 v[88:89], 0
	v_mov_b64_e32 v[90:91], 0
	v_mov_b64_e32 v[92:93], 0
	v_mov_b64_e32 v[94:95], 0
	v_mov_b64_e32 v[96:97], 0
	v_mov_b64_e32 v[98:99], 0
	v_mov_b64_e32 v[100:101], 0
	v_mov_b64_e32 v[102:103], 0
	v_mov_b64_e32 v[104:105], 0
	v_mov_b64_e32 v[106:107], 0
	v_mov_b64_e32 v[108:109], 0
	v_mov_b64_e32 v[110:111], 0
	v_mov_b64_e32 v[112:113], 0
	v_mov_b64_e32 v[114:115], 0
	v_mov_b64_e32 v[116:117], 0
	v_mov_b64_e32 v[118:119], 0
	v_mov_b64_e32 v[120:121], 0
	v_mov_b64_e32 v[122:123], 0
	v_mov_b64_e32 v[124:125], 0
	v_mov_b64_e32 v[126:127], 0

.LBB0_874:
	s_ashr_i32 s61, s60, 31
	s_lshl_b64 s[66:67], s[60:61], 11
	s_add_u32 s66, s34, s66
	s_addc_u32 s67, s35, s67
	s_and_b64 s[68:69], s[62:63], exec
	s_cselect_b32 s3, s67, s85
	s_cselect_b32 s61, s66, s84
	s_ashr_i32 s65, s64, 31
	s_lshl_b64 s[68:69], s[64:65], 11
	s_add_u32 s78, s19, s68
	s_addc_u32 s79, s40, s69
	s_and_b64 s[68:69], s[62:63], exec
	s_cselect_b32 s65, s79, s87
	s_cselect_b32 s73, s78, s86
	s_cmp_lg_u32 s4, 0
	s_cselect_b64 s[82:83], -1, 0
	s_add_u32 s69, s86, 0x100
	s_addc_u32 s71, s87, 0
	s_cmp_eq_u32 s4, 0
	s_cbranch_scc1 .LBB0_878
	s_add_u32 s4, s84, 0x100
	s_addc_u32 s5, s85, 0
	s_add_u32 s86, s86, 0x80080
	v_mov_b32_e32 v0, 0
	s_addc_u32 s87, s87, 0
	s_mov_b32 s68, -2
	v_mov_b32_e32 v1, v0
	v_mov_b32_e32 v2, v0
	v_mov_b32_e32 v3, v0
	v_mov_b32_e32 v4, v0
	v_mov_b32_e32 v5, v0
	v_mov_b32_e32 v6, v0
	v_mov_b32_e32 v7, v0
	v_mov_b32_e32 v8, v0
	v_mov_b32_e32 v9, v0
	v_mov_b32_e32 v10, v0
	v_mov_b32_e32 v11, v0
	v_mov_b32_e32 v12, v0
	v_mov_b32_e32 v13, v0
	v_mov_b32_e32 v14, v0
	v_mov_b32_e32 v15, v0
	v_mov_b32_e32 v16, v0
	v_mov_b32_e32 v17, v0
	v_mov_b32_e32 v18, v0
	v_mov_b32_e32 v19, v0
	v_mov_b32_e32 v20, v0
	v_mov_b32_e32 v21, v0
	v_mov_b32_e32 v22, v0
	v_mov_b32_e32 v23, v0
	v_mov_b32_e32 v24, v0
	v_mov_b32_e32 v25, v0
	v_mov_b32_e32 v26, v0
	v_mov_b32_e32 v27, v0
	v_mov_b32_e32 v28, v0
	v_mov_b32_e32 v29, v0
	v_mov_b32_e32 v30, v0
	v_mov_b32_e32 v31, v0
	v_mov_b32_e32 v32, v0
	v_mov_b32_e32 v33, v0
	v_mov_b32_e32 v34, v0
	v_mov_b32_e32 v35, v0

	v_mov_b64_e32 v[36:37], 0
	v_mov_b64_e32 v[38:39], 0
	v_mov_b64_e32 v[40:41], 0
	v_mov_b64_e32 v[42:43], 0
	v_mov_b64_e32 v[44:45], 0
	v_mov_b64_e32 v[46:47], 0
	v_mov_b64_e32 v[48:49], 0
	v_mov_b64_e32 v[50:51], 0
	v_mov_b64_e32 v[52:53], 0
	v_mov_b64_e32 v[54:55], 0
	v_mov_b64_e32 v[56:57], 0
	v_mov_b64_e32 v[58:59], 0
	v_mov_b64_e32 v[60:61], 0
	v_mov_b64_e32 v[62:63], 0
	v_mov_b64_e32 v[64:65], 0
	v_mov_b64_e32 v[66:67], 0
	v_mov_b64_e32 v[68:69], 0
	v_mov_b64_e32 v[70:71], 0
	v_mov_b64_e32 v[72:73], 0
	v_mov_b64_e32 v[74:75], 0
	v_mov_b64_e32 v[76:77], 0
	v_mov_b64_e32 v[78:79], 0
	v_mov_b64_e32 v[80:81], 0
	v_mov_b64_e32 v[82:83], 0
	v_mov_b64_e32 v[84:85], 0
	v_mov_b64_e32 v[86:87], 0
	v_mov_b64_e32 v[88:89], 0
	v_mov_b64_e32 v[90:91], 0
	v_mov_b64_e32 v[92:93], 0
	v_mov_b64_e32 v[94:95], 0

.LBB0_879:
	v_mov_b32_e32 v127, 0
	s_and_b64 vcc, exec, s[86:87]
	v_mov_b32_e32 v126, v127
	v_mov_b32_e32 v125, v127
	v_mov_b32_e32 v124, v127
	v_mov_b32_e32 v123, v127
	v_mov_b32_e32 v122, v127
	v_mov_b32_e32 v121, v127
	v_mov_b32_e32 v120, v127
	v_mov_b32_e32 v119, v127
	v_mov_b32_e32 v118, v127
	v_mov_b32_e32 v117, v127
	v_mov_b32_e32 v116, v127
	v_mov_b32_e32 v115, v127
	v_mov_b32_e32 v114, v127
	v_mov_b32_e32 v113, v127
	v_mov_b32_e32 v112, v127
	v_mov_b32_e32 v111, v127
	v_mov_b32_e32 v110, v127
	v_mov_b32_e32 v109, v127
	v_mov_b32_e32 v108, v127
	v_mov_b32_e32 v107, v127
	v_mov_b32_e32 v106, v127
	v_mov_b32_e32 v105, v127
	v_mov_b32_e32 v104, v127
	v_mov_b32_e32 v103, v127
	v_mov_b32_e32 v102, v127
	v_mov_b32_e32 v101, v127
	v_mov_b32_e32 v100, v127
	v_mov_b32_e32 v99, v127
	v_mov_b32_e32 v98, v127
	v_mov_b32_e32 v97, v127
	v_mov_b32_e32 v96, v127
	s_cbranch_vccz .LBB0_882
	s_cmp_lg_u32 s96, 0
	s_cselect_b64 s[86:87], -1, 0
	s_add_u32 s68, s73, 0x80000
	s_addc_u32 s4, s65, 0
	s_add_u32 s84, s84, 0x40080
	v_mov_b32_e32 v96, 0
	s_addc_u32 s85, s85, 0
	s_mov_b32 s5, -2
	v_mov_b64_e32 v[0:1], 0
	v_mov_b64_e32 v[2:3], 0
	v_mov_b64_e32 v[4:5], 0
	v_mov_b64_e32 v[6:7], 0
	v_mov_b64_e32 v[8:9], 0
	v_mov_b64_e32 v[10:11], 0
	v_mov_b64_e32 v[12:13], 0
	v_mov_b64_e32 v[14:15], 0
	v_mov_b64_e32 v[16:17], 0
	v_mov_b64_e32 v[18:19], 0
	v_mov_b64_e32 v[20:21], 0
	v_mov_b64_e32 v[22:23], 0
	v_mov_b64_e32 v[24:25], 0
	v_mov_b64_e32 v[26:27], 0
	v_mov_b64_e32 v[28:29], 0
	v_mov_b64_e32 v[30:31], 0
	v_mov_b64_e32 v[32:33], 0
	v_mov_b64_e32 v[34:35], 0
	v_mov_b32_e32 v97, 0
	v_mov_b64_e32 v[98:99], 0
	v_mov_b64_e32 v[100:101], 0
	v_mov_b64_e32 v[102:103], 0
	v_mov_b64_e32 v[104:105], 0
	v_mov_b64_e32 v[106:107], 0
	v_mov_b64_e32 v[108:109], 0
	v_mov_b64_e32 v[110:111], 0
	v_mov_b64_e32 v[112:113], 0
	v_mov_b64_e32 v[114:115], 0
	v_mov_b64_e32 v[116:117], 0
	v_mov_b64_e32 v[118:119], 0
	v_mov_b64_e32 v[120:121], 0
	v_mov_b64_e32 v[122:123], 0
	v_mov_b64_e32 v[124:125], 0
	v_mov_b64_e32 v[126:127], 0

	v_mov_b64_e32 v[36:37], 0
	v_mov_b64_e32 v[38:39], 0
	v_mov_b64_e32 v[40:41], 0
	v_mov_b64_e32 v[42:43], 0
	v_mov_b64_e32 v[44:45], 0
	v_mov_b64_e32 v[46:47], 0
	v_mov_b64_e32 v[48:49], 0
	v_mov_b64_e32 v[50:51], 0
	v_mov_b64_e32 v[52:53], 0
	v_mov_b64_e32 v[54:55], 0
	v_mov_b64_e32 v[56:57], 0
	v_mov_b64_e32 v[58:59], 0
	v_mov_b64_e32 v[60:61], 0
	v_mov_b64_e32 v[62:63], 0
	v_mov_b64_e32 v[64:65], 0
	v_mov_b64_e32 v[66:67], 0
	v_mov_b64_e32 v[68:69], 0
	v_mov_b64_e32 v[70:71], 0
	v_mov_b64_e32 v[72:73], 0
	v_mov_b64_e32 v[74:75], 0
	v_mov_b64_e32 v[76:77], 0
	v_mov_b64_e32 v[78:79], 0
	v_mov_b64_e32 v[80:81], 0
	v_mov_b64_e32 v[82:83], 0
	v_mov_b64_e32 v[84:85], 0
	v_mov_b64_e32 v[86:87], 0
	v_mov_b64_e32 v[88:89], 0
	v_mov_b64_e32 v[90:91], 0
	v_mov_b64_e32 v[92:93], 0
	v_mov_b64_e32 v[94:95], 0

.LBB0_1529:
	s_ashr_i32 s11, s10, 31
	v_cmp_lt_i64_e32 vcc, s[14:15], v[164:165]
	s_lshl_b64 s[14:15], s[10:11], 11
	s_add_u32 s14, s41, s14
	s_addc_u32 s15, s42, s15
	s_and_b64 s[18:19], vcc, exec
	s_cselect_b32 s11, s15, s25
	s_cselect_b32 s61, s14, s24
	s_ashr_i32 s13, s12, 31
	s_lshl_b64 s[18:19], s[12:13], 11
	s_add_u32 s18, s43, s18
	s_addc_u32 s19, s44, s19
	s_and_b64 s[38:39], vcc, exec
	s_cselect_b32 s13, s19, s37
	s_cselect_b32 s62, s18, s36
	s_add_u32 s24, s24, 0x40080
	s_addc_u32 s25, s25, 0
	s_add_u32 s63, s36, 0x100
	v_mov_b32_e32 v0, 0
	s_addc_u32 s64, s37, 0
	s_mov_b32 s65, -2
	s_waitcnt lgkmcnt(0)
	v_mov_b32_e32 v1, v0
	v_mov_b32_e32 v2, v0
	v_mov_b32_e32 v3, v0
	v_mov_b32_e32 v4, v0
	v_mov_b32_e32 v5, v0
	v_mov_b32_e32 v6, v0
	v_mov_b32_e32 v7, v0
	v_mov_b32_e32 v16, v0
	v_mov_b32_e32 v17, v0
	v_mov_b32_e32 v18, v0
	v_mov_b32_e32 v19, v0
	v_mov_b32_e32 v20, v0
	v_mov_b32_e32 v21, v0
	v_mov_b32_e32 v22, v0
	v_mov_b32_e32 v23, v0
	v_mov_b32_e32 v32, v0
	v_mov_b32_e32 v33, v0
	v_mov_b32_e32 v34, v0
	v_mov_b32_e32 v35, v0

	v_mov_b64_e32 v[8:9], 0
	v_mov_b64_e32 v[10:11], 0
	v_mov_b64_e32 v[12:13], 0
	v_mov_b64_e32 v[14:15], 0
	v_mov_b64_e32 v[24:25], 0
	v_mov_b64_e32 v[26:27], 0
	v_mov_b64_e32 v[28:29], 0
	v_mov_b64_e32 v[30:31], 0
	v_mov_b64_e32 v[36:37], 0
	v_mov_b64_e32 v[38:39], 0
	v_mov_b64_e32 v[40:41], 0
	v_mov_b64_e32 v[42:43], 0
	v_mov_b64_e32 v[44:45], 0
	v_mov_b64_e32 v[46:47], 0
	v_mov_b64_e32 v[48:49], 0
	v_mov_b64_e32 v[50:51], 0
	v_mov_b64_e32 v[52:53], 0
	v_mov_b64_e32 v[54:55], 0
	v_mov_b64_e32 v[56:57], 0
	v_mov_b64_e32 v[58:59], 0
	v_mov_b64_e32 v[60:61], 0
	v_mov_b64_e32 v[62:63], 0
	v_mov_b64_e32 v[64:65], 0
	v_mov_b64_e32 v[66:67], 0
	v_mov_b64_e32 v[68:69], 0
	v_mov_b64_e32 v[70:71], 0
	v_mov_b64_e32 v[72:73], 0
	v_mov_b64_e32 v[74:75], 0
	v_mov_b64_e32 v[76:77], 0
	v_mov_b64_e32 v[78:79], 0
	v_mov_b64_e32 v[80:81], 0
	v_mov_b64_e32 v[82:83], 0
	v_mov_b64_e32 v[84:85], 0
	v_mov_b64_e32 v[86:87], 0
	v_mov_b64_e32 v[88:89], 0
	v_mov_b64_e32 v[90:91], 0
	v_mov_b64_e32 v[92:93], 0
	v_mov_b64_e32 v[94:95], 0
	v_mov_b64_e32 v[96:97], 0
	v_mov_b64_e32 v[98:99], 0
	v_mov_b64_e32 v[100:101], 0
	v_mov_b64_e32 v[102:103], 0
	v_mov_b64_e32 v[104:105], 0
	v_mov_b64_e32 v[106:107], 0
	v_mov_b64_e32 v[108:109], 0
	v_mov_b64_e32 v[110:111], 0
	v_mov_b64_e32 v[112:113], 0
	v_mov_b64_e32 v[114:115], 0
	v_mov_b64_e32 v[116:117], 0
	v_mov_b64_e32 v[118:119], 0
	v_mov_b64_e32 v[120:121], 0
	v_mov_b64_e32 v[122:123], 0
	v_mov_b64_e32 v[124:125], 0
	v_mov_b64_e32 v[126:127], 0

.LBB0_1747:
	s_ashr_i32 s49, s48, 31
	s_lshl_b64 s[6:7], s[48:49], 11
	s_add_u32 s56, s34, s6
	s_addc_u32 s57, s35, s7
	s_and_b64 s[6:7], s[50:51], exec
	s_cselect_b32 s3, s57, s9
	s_cselect_b32 s5, s56, s8
	s_ashr_i32 s55, s54, 31
	s_lshl_b64 s[6:7], s[54:55], 11
	s_add_u32 s58, s45, s6
	s_addc_u32 s59, s47, s7
	s_and_b64 s[6:7], s[50:51], exec
	s_cselect_b32 s49, s59, s61
	s_cselect_b32 s52, s58, s60
	s_cmp_lg_u32 s62, 0
	s_cselect_b64 s[6:7], -1, 0
	s_add_u32 s53, s60, 0x100
	s_addc_u32 s55, s61, 0
	s_cmp_eq_u32 s62, 0
	s_cbranch_scc1 .LBB0_1800
	s_add_u32 s64, s8, 0x100
	s_addc_u32 s65, s9, 0
	s_add_u32 s60, s60, 0x80080
	v_mov_b32_e32 v14, 0
	s_addc_u32 s61, s61, 0
	s_mov_b32 s66, -2
	v_mov_b32_e32 v15, v14
	v_mov_b32_e32 v16, v14
	v_mov_b32_e32 v17, v14
	v_mov_b32_e32 v22, v14
	v_mov_b32_e32 v23, v14
	v_mov_b32_e32 v24, v14
	v_mov_b32_e32 v25, v14
	v_mov_b32_e32 v34, v14
	v_mov_b32_e32 v35, v14

	v_mov_b64_e32 v[36:37], 0
	v_mov_b64_e32 v[42:43], 0
	v_mov_b64_e32 v[44:45], 0
	v_mov_b64_e32 v[50:51], 0
	v_mov_b64_e32 v[52:53], 0
	v_mov_b64_e32 v[54:55], 0
	v_mov_b64_e32 v[56:57], 0
	v_mov_b64_e32 v[58:59], 0
	v_mov_b64_e32 v[60:61], 0
	v_mov_b64_e32 v[62:63], 0
	v_mov_b64_e32 v[64:65], 0
	v_mov_b64_e32 v[66:67], 0
	v_mov_b64_e32 v[68:69], 0
	v_mov_b64_e32 v[70:71], 0
	v_mov_b64_e32 v[72:73], 0
	v_mov_b64_e32 v[74:75], 0
	v_mov_b64_e32 v[76:77], 0
	v_mov_b64_e32 v[78:79], 0
	v_mov_b64_e32 v[80:81], 0
	v_mov_b64_e32 v[82:83], 0
	v_mov_b64_e32 v[84:85], 0
	v_mov_b64_e32 v[86:87], 0
	v_mov_b64_e32 v[88:89], 0
	v_mov_b64_e32 v[90:91], 0
	v_mov_b64_e32 v[92:93], 0
	v_mov_b64_e32 v[94:95], 0
	v_mov_b64_e32 v[96:97], 0
	v_mov_b64_e32 v[98:99], 0
	v_mov_b64_e32 v[100:101], 0
	v_mov_b64_e32 v[102:103], 0
	v_mov_b64_e32 v[104:105], 0
	v_mov_b64_e32 v[106:107], 0
	v_mov_b64_e32 v[108:109], 0
	v_mov_b64_e32 v[110:111], 0
	v_mov_b64_e32 v[112:113], 0
	v_mov_b64_e32 v[114:115], 0
	v_mov_b64_e32 v[116:117], 0
	v_mov_b64_e32 v[118:119], 0
	v_mov_b64_e32 v[120:121], 0
	v_mov_b64_e32 v[122:123], 0
	v_mov_b64_e32 v[124:125], 0
	v_mov_b64_e32 v[126:127], 0
	v_mov_b64_e32 v[128:129], 0

.LBB0_1751:
	s_cmp_lg_u32 s92, 0
	s_cselect_b64 s[60:61], -1, 0
	s_add_u32 s68, s52, 0x80000
	s_addc_u32 s69, s49, 0
	s_add_u32 s8, s8, 0x40080
	v_mov_b32_e32 v2, 0
	s_addc_u32 s9, s9, 0
	s_mov_b32 s72, -2
	v_mov_b32_e32 v3, v2
	v_mov_b32_e32 v4, v2
	v_mov_b32_e32 v5, v2
	v_mov_b32_e32 v6, v2
	v_mov_b32_e32 v7, v2
	v_mov_b32_e32 v8, v2
	v_mov_b32_e32 v9, v2
	v_mov_b32_e32 v10, v2
	v_mov_b32_e32 v11, v2
	v_mov_b32_e32 v12, v2
	v_mov_b32_e32 v13, v2
	v_mov_b32_e32 v18, v2
	v_mov_b32_e32 v19, v2
	v_mov_b32_e32 v20, v2
	v_mov_b32_e32 v21, v2
	v_mov_b32_e32 v26, v2
	v_mov_b32_e32 v27, v2
	v_mov_b32_e32 v28, v2
	v_mov_b32_e32 v29, v2
	v_mov_b32_e32 v30, v2
	v_mov_b32_e32 v31, v2
	v_mov_b32_e32 v32, v2
	v_mov_b32_e32 v33, v2

	v_mov_b64_e32 v[14:15], 0
	v_mov_b64_e32 v[16:17], 0
	v_mov_b64_e32 v[22:23], 0
	v_mov_b64_e32 v[24:25], 0
	v_mov_b64_e32 v[34:35], 0
	v_mov_b64_e32 v[36:37], 0
	v_mov_b64_e32 v[38:39], 0
	v_mov_b64_e32 v[40:41], 0
	v_mov_b64_e32 v[42:43], 0
	v_mov_b64_e32 v[44:45], 0
	v_mov_b64_e32 v[46:47], 0
	v_mov_b64_e32 v[48:49], 0
	v_mov_b64_e32 v[50:51], 0
	v_mov_b64_e32 v[52:53], 0
	v_mov_b64_e32 v[54:55], 0
	v_mov_b64_e32 v[56:57], 0
	v_mov_b64_e32 v[58:59], 0
	v_mov_b64_e32 v[60:61], 0
	v_mov_b64_e32 v[62:63], 0
	v_mov_b64_e32 v[64:65], 0
	v_mov_b64_e32 v[66:67], 0
	v_mov_b64_e32 v[68:69], 0
	v_mov_b64_e32 v[70:71], 0
	v_mov_b64_e32 v[72:73], 0
	v_mov_b64_e32 v[74:75], 0
	v_mov_b64_e32 v[76:77], 0
	v_mov_b64_e32 v[78:79], 0
	v_mov_b64_e32 v[80:81], 0
	v_mov_b64_e32 v[82:83], 0
	v_mov_b64_e32 v[84:85], 0
	v_mov_b64_e32 v[86:87], 0
	v_mov_b64_e32 v[88:89], 0
	v_mov_b64_e32 v[90:91], 0
	v_mov_b64_e32 v[92:93], 0
	v_mov_b64_e32 v[94:95], 0
	v_mov_b64_e32 v[96:97], 0
	v_mov_b64_e32 v[98:99], 0
	v_mov_b64_e32 v[100:101], 0
	v_mov_b64_e32 v[102:103], 0
	v_mov_b64_e32 v[104:105], 0
	v_mov_b64_e32 v[106:107], 0
	v_mov_b64_e32 v[108:109], 0
	v_mov_b64_e32 v[110:111], 0
	v_mov_b64_e32 v[112:113], 0
	v_mov_b64_e32 v[114:115], 0
	v_mov_b64_e32 v[116:117], 0
	v_mov_b64_e32 v[118:119], 0
	v_mov_b64_e32 v[120:121], 0
	v_mov_b64_e32 v[122:123], 0
	v_mov_b64_e32 v[124:125], 0
	v_mov_b64_e32 v[126:127], 0
	v_mov_b64_e32 v[128:129], 0

.LBB0_1881:
	s_add_u32 s56, s24, 0x100
	v_mov_b32_e32 v0, 0
	s_addc_u32 s57, s25, 0
	s_mov_b32 s58, -2
	v_mov_b32_e32 v1, v0
	v_mov_b32_e32 v2, v0
	v_mov_b32_e32 v3, v0
	v_mov_b32_e32 v4, v0
	v_mov_b32_e32 v5, v0
	v_mov_b32_e32 v6, v0
	v_mov_b32_e32 v7, v0
	v_mov_b32_e32 v16, v0
	v_mov_b32_e32 v17, v0
	v_mov_b32_e32 v18, v0
	v_mov_b32_e32 v19, v0
	v_mov_b32_e32 v20, v0
	v_mov_b32_e32 v21, v0
	v_mov_b32_e32 v22, v0
	v_mov_b32_e32 v23, v0
	v_mov_b32_e32 v32, v0
	v_mov_b32_e32 v33, v0
	v_mov_b32_e32 v34, v0
	v_mov_b32_e32 v35, v0

	v_mov_b64_e32 v[8:9], 0
	v_mov_b64_e32 v[10:11], 0
	v_mov_b64_e32 v[12:13], 0
	v_mov_b64_e32 v[14:15], 0
	v_mov_b64_e32 v[24:25], 0
	v_mov_b64_e32 v[26:27], 0
	v_mov_b64_e32 v[28:29], 0
	v_mov_b64_e32 v[30:31], 0
	v_mov_b64_e32 v[36:37], 0
	v_mov_b64_e32 v[38:39], 0
	v_mov_b64_e32 v[40:41], 0
	v_mov_b64_e32 v[42:43], 0
	v_mov_b64_e32 v[44:45], 0
	v_mov_b64_e32 v[46:47], 0
	v_mov_b64_e32 v[48:49], 0
	v_mov_b64_e32 v[50:51], 0
	v_mov_b64_e32 v[52:53], 0
	v_mov_b64_e32 v[54:55], 0
	v_mov_b64_e32 v[56:57], 0
	v_mov_b64_e32 v[58:59], 0
	v_mov_b64_e32 v[60:61], 0
	v_mov_b64_e32 v[62:63], 0
	v_mov_b64_e32 v[64:65], 0
	v_mov_b64_e32 v[66:67], 0
	v_mov_b64_e32 v[68:69], 0
	v_mov_b64_e32 v[70:71], 0
	v_mov_b64_e32 v[72:73], 0
	v_mov_b64_e32 v[74:75], 0
	v_mov_b64_e32 v[76:77], 0
	v_mov_b64_e32 v[78:79], 0
	v_mov_b64_e32 v[80:81], 0
	v_mov_b64_e32 v[82:83], 0
	v_mov_b64_e32 v[84:85], 0
	v_mov_b64_e32 v[86:87], 0
	v_mov_b64_e32 v[88:89], 0
	v_mov_b64_e32 v[90:91], 0
	v_mov_b64_e32 v[92:93], 0
	v_mov_b64_e32 v[94:95], 0
	v_mov_b64_e32 v[96:97], 0
	v_mov_b64_e32 v[98:99], 0
	v_mov_b64_e32 v[100:101], 0
	v_mov_b64_e32 v[102:103], 0
	v_mov_b64_e32 v[104:105], 0
	v_mov_b64_e32 v[106:107], 0
	v_mov_b64_e32 v[108:109], 0
	v_mov_b64_e32 v[110:111], 0
	v_mov_b64_e32 v[112:113], 0
	v_mov_b64_e32 v[114:115], 0
	v_mov_b64_e32 v[116:117], 0
	v_mov_b64_e32 v[118:119], 0
	v_mov_b64_e32 v[120:121], 0
	v_mov_b64_e32 v[122:123], 0
	v_mov_b64_e32 v[124:125], 0
	v_mov_b64_e32 v[126:127], 0
